# v013 + SGPR-base (saddr) LDS-DMA addressing in FFN-up loop (removes 16 64-bit VALU address adds per iteration)
# speedup vs baseline: 1.0362x; 1.0058x over previous
.Lsp_LBB0269:
	s_or_b32 s54, s35, 1
	s_lshl_b64 s[16:17], s[54:55], 7
	s_add_i32 s54, s35, 2
	s_lshl_b64 s[44:45], s[54:55], 7
	s_add_u32 s46, s66, s44
	s_addc_u32 s47, s67, s45
	s_and_b64 vcc, s[14:15], exec
	s_cselect_b32 vcc_hi, s29, s47
	s_cselect_b32 vcc_lo, s65, s46
	s_add_u32 s44, s70, s44
	s_addc_u32 s45, s71, s45
	s_and_b64 s[14:15], s[14:15], exec
	s_cselect_b32 s15, s51, s45
	s_cselect_b32 s14, s30, s44
	s_add_i32 s44, 0, 0x10000
	v_add_u32_e32 v143, s44, v140
	s_add_i32 s45, 0, 0x14000
	s_add_u32 s16, s31, s16
	s_addc_u32 s17, s34, s17
	s_add_i32 m0, s73, 0xc000
	v_add_u32_e32 v143, s44, v140
	ds_read_b128 v[136:139], v143
	ds_read_b128 v[144:147], v143 offset:1024
	ds_read_b128 v[148:151], v143 offset:2048
	ds_read_b128 v[152:155], v143 offset:3072
	v_add_u32_e32 v143, s45, v140
	ds_read_b128 v[168:171], v143
	ds_read_b128 v[172:175], v143 offset:1024
	ds_read_b128 v[176:179], v143 offset:2048
	ds_read_b128 v[180:183], v143 offset:3072
	ds_read_b128 v[184:187], v142
	ds_read_b128 v[188:191], v142 offset:1024
	ds_read_b128 v[192:195], v142 offset:2048
	ds_read_b128 v[196:199], v142 offset:3072
	ds_read_b128 v[200:203], v142 offset:4096
	ds_read_b128 v[204:207], v142 offset:5120
	ds_read_b128 v[216:219], v142 offset:6144
	ds_read_b128 v[220:223], v142 offset:7168
	global_load_lds_dwordx4 v130, s[16:17]
	s_add_i32 m0, s73, 0xe000
	s_nop 0
	global_load_lds_dwordx4 v132, s[16:17]
	s_waitcnt vmcnt(8)
	s_waitcnt lgkmcnt(0)
	s_barrier
	s_waitcnt lgkmcnt(0)
	v_mfma_f32_16x16x32_bf16 v[122:125], v[136:139], v[184:187], v[122:125]
	v_mfma_f32_16x16x32_bf16 v[122:125], v[144:147], v[188:191], v[122:125]
	v_mfma_f32_16x16x32_bf16 v[114:117], v[148:151], v[184:187], v[114:117]
	v_mfma_f32_16x16x32_bf16 v[114:117], v[152:155], v[188:191], v[114:117]
	v_mfma_f32_16x16x32_bf16 v[106:109], v[136:139], v[192:195], v[106:109]
	v_mfma_f32_16x16x32_bf16 v[106:109], v[144:147], v[196:199], v[106:109]
	v_mfma_f32_16x16x32_bf16 v[102:105], v[148:151], v[192:195], v[102:105]
	v_mfma_f32_16x16x32_bf16 v[102:105], v[152:155], v[196:199], v[102:105]
	v_mfma_f32_16x16x32_bf16 v[90:93], v[136:139], v[200:203], v[90:93]
	v_mfma_f32_16x16x32_bf16 v[90:93], v[144:147], v[204:207], v[90:93]
	v_mfma_f32_16x16x32_bf16 v[86:89], v[148:151], v[200:203], v[86:89]
	v_mfma_f32_16x16x32_bf16 v[86:89], v[152:155], v[204:207], v[86:89]
	v_mfma_f32_16x16x32_bf16 v[74:77], v[136:139], v[216:219], v[74:77]
	v_mfma_f32_16x16x32_bf16 v[74:77], v[144:147], v[220:223], v[74:77]
	v_mfma_f32_16x16x32_bf16 v[70:73], v[148:151], v[216:219], v[70:73]
	v_mfma_f32_16x16x32_bf16 v[70:73], v[152:155], v[220:223], v[70:73]
	v_mfma_f32_16x16x32_bf16 v[126:129], v[168:171], v[184:187], v[126:129]
	v_mfma_f32_16x16x32_bf16 v[126:129], v[172:175], v[188:191], v[126:129]
	v_mfma_f32_16x16x32_bf16 v[118:121], v[176:179], v[184:187], v[118:121]
	v_mfma_f32_16x16x32_bf16 v[118:121], v[180:183], v[188:191], v[118:121]
	v_mfma_f32_16x16x32_bf16 v[110:113], v[168:171], v[192:195], v[110:113]
	v_mfma_f32_16x16x32_bf16 v[110:113], v[172:175], v[196:199], v[110:113]
	v_mfma_f32_16x16x32_bf16 v[98:101], v[176:179], v[192:195], v[98:101]
	v_mfma_f32_16x16x32_bf16 v[98:101], v[180:183], v[196:199], v[98:101]
	v_mfma_f32_16x16x32_bf16 v[94:97], v[168:171], v[200:203], v[94:97]
	v_mfma_f32_16x16x32_bf16 v[94:97], v[172:175], v[204:207], v[94:97]
	v_mfma_f32_16x16x32_bf16 v[82:85], v[176:179], v[200:203], v[82:85]
	v_mfma_f32_16x16x32_bf16 v[82:85], v[180:183], v[204:207], v[82:85]
	v_mfma_f32_16x16x32_bf16 v[78:81], v[168:171], v[216:219], v[78:81]
	v_mfma_f32_16x16x32_bf16 v[78:81], v[172:175], v[220:223], v[78:81]
	v_mfma_f32_16x16x32_bf16 v[66:69], v[176:179], v[216:219], v[66:69]
	v_mfma_f32_16x16x32_bf16 v[66:69], v[180:183], v[220:223], v[66:69]
	s_barrier
	s_add_i32 s16, s44, s61
	s_mov_b32 m0, s16
	ds_read_b128 v[184:187], v142 offset:16384
	ds_read_b128 v[188:191], v142 offset:17408
	ds_read_b128 v[192:195], v142 offset:18432
	ds_read_b128 v[196:199], v142 offset:19456
	ds_read_b128 v[200:203], v142 offset:20480
	ds_read_b128 v[204:207], v142 offset:21504
	ds_read_b128 v[216:219], v142 offset:22528
	ds_read_b128 v[220:223], v142 offset:23552
	global_load_lds_dwordx4 v158, s[14:15]
	s_add_i32 m0, s16, 0x2000
	s_nop 0
	global_load_lds_dwordx4 v134, s[14:15]
	s_add_u32 s16, s14, 0x80000
	s_addc_u32 s17, s15, 0
	s_add_i32 s44, s45, s61
	s_mov_b32 m0, s44
	s_nop 0
	global_load_lds_dwordx4 v158, s[16:17]
	s_add_i32 m0, s44, 0x2000
	s_nop 0
	global_load_lds_dwordx4 v134, s[16:17]
	s_mov_b32 m0, s73
	s_nop 0
	global_load_lds_dwordx4 v130, vcc
	s_mov_b32 m0, s75
	s_nop 0
	global_load_lds_dwordx4 v132, vcc
	s_waitcnt vmcnt(8)
	s_waitcnt lgkmcnt(0)
	s_barrier
	s_waitcnt lgkmcnt(0)
	v_mfma_f32_16x16x32_bf16 v[58:61], v[136:139], v[184:187], v[58:61]
	v_mfma_f32_16x16x32_bf16 v[58:61], v[144:147], v[188:191], v[58:61]
	v_mfma_f32_16x16x32_bf16 v[54:57], v[148:151], v[184:187], v[54:57]
	v_mfma_f32_16x16x32_bf16 v[54:57], v[152:155], v[188:191], v[54:57]
	v_mfma_f32_16x16x32_bf16 v[42:45], v[136:139], v[192:195], v[42:45]
	v_mfma_f32_16x16x32_bf16 v[42:45], v[144:147], v[196:199], v[42:45]
	v_mfma_f32_16x16x32_bf16 v[38:41], v[148:151], v[192:195], v[38:41]
	v_mfma_f32_16x16x32_bf16 v[38:41], v[152:155], v[196:199], v[38:41]
	v_mfma_f32_16x16x32_bf16 v[26:29], v[136:139], v[200:203], v[26:29]
	v_mfma_f32_16x16x32_bf16 v[26:29], v[144:147], v[204:207], v[26:29]
	v_mfma_f32_16x16x32_bf16 v[22:25], v[148:151], v[200:203], v[22:25]
	v_mfma_f32_16x16x32_bf16 v[22:25], v[152:155], v[204:207], v[22:25]
	v_mfma_f32_16x16x32_bf16 v[10:13], v[136:139], v[216:219], v[10:13]
	v_mfma_f32_16x16x32_bf16 v[10:13], v[144:147], v[220:223], v[10:13]
	v_mfma_f32_16x16x32_bf16 v[2:5], v[148:151], v[216:219], v[2:5]
	v_mfma_f32_16x16x32_bf16 v[2:5], v[152:155], v[220:223], v[2:5]
	v_mfma_f32_16x16x32_bf16 v[62:65], v[168:171], v[184:187], v[62:65]
	v_mfma_f32_16x16x32_bf16 v[62:65], v[172:175], v[188:191], v[62:65]
	v_mfma_f32_16x16x32_bf16 v[50:53], v[176:179], v[184:187], v[50:53]
	v_mfma_f32_16x16x32_bf16 v[50:53], v[180:183], v[188:191], v[50:53]
	v_mfma_f32_16x16x32_bf16 v[46:49], v[168:171], v[192:195], v[46:49]
	v_mfma_f32_16x16x32_bf16 v[46:49], v[172:175], v[196:199], v[46:49]
	v_mfma_f32_16x16x32_bf16 v[34:37], v[176:179], v[192:195], v[34:37]
	v_mfma_f32_16x16x32_bf16 v[34:37], v[180:183], v[196:199], v[34:37]
	v_mfma_f32_16x16x32_bf16 v[30:33], v[168:171], v[200:203], v[30:33]
	v_mfma_f32_16x16x32_bf16 v[30:33], v[172:175], v[204:207], v[30:33]
	v_mfma_f32_16x16x32_bf16 v[18:21], v[176:179], v[200:203], v[18:21]
	v_mfma_f32_16x16x32_bf16 v[18:21], v[180:183], v[204:207], v[18:21]
	v_mfma_f32_16x16x32_bf16 v[14:17], v[168:171], v[216:219], v[14:17]
	v_mfma_f32_16x16x32_bf16 v[14:17], v[172:175], v[220:223], v[14:17]
	v_mfma_f32_16x16x32_bf16 v[6:9], v[176:179], v[216:219], v[6:9]
	v_mfma_f32_16x16x32_bf16 v[6:9], v[180:183], v[220:223], v[6:9]
	s_barrier
	s_add_i32 s44, 0, 0x18000
	s_add_i32 s45, 0, 0x1c000
	s_add_u32 s16, vcc_lo, 0x80000
	s_addc_u32 s17, vcc_hi, 0
	s_mov_b32 m0, s24
	v_add_u32_e32 v143, s44, v140
	ds_read_b128 v[136:139], v143
	ds_read_b128 v[144:147], v143 offset:1024
	ds_read_b128 v[148:151], v143 offset:2048
	ds_read_b128 v[152:155], v143 offset:3072
	v_add_u32_e32 v143, s45, v140
	ds_read_b128 v[168:171], v143
	ds_read_b128 v[172:175], v143 offset:1024
	ds_read_b128 v[176:179], v143 offset:2048
	ds_read_b128 v[180:183], v143 offset:3072
	ds_read_b128 v[184:187], v142 offset:32768
	ds_read_b128 v[188:191], v142 offset:33792
	ds_read_b128 v[192:195], v142 offset:34816
	ds_read_b128 v[196:199], v142 offset:35840
	ds_read_b128 v[200:203], v142 offset:36864
	ds_read_b128 v[204:207], v142 offset:37888
	ds_read_b128 v[216:219], v142 offset:38912
	ds_read_b128 v[220:223], v142 offset:39936
	global_load_lds_dwordx4 v130, s[16:17]
	s_mov_b32 m0, s25
	s_nop 0
	global_load_lds_dwordx4 v132, s[16:17]
	s_waitcnt vmcnt(8)
	s_waitcnt lgkmcnt(0)
	s_barrier
	s_waitcnt lgkmcnt(0)
	v_mfma_f32_16x16x32_bf16 v[122:125], v[136:139], v[184:187], v[122:125]
	v_mfma_f32_16x16x32_bf16 v[122:125], v[144:147], v[188:191], v[122:125]
	v_mfma_f32_16x16x32_bf16 v[114:117], v[148:151], v[184:187], v[114:117]
	v_mfma_f32_16x16x32_bf16 v[114:117], v[152:155], v[188:191], v[114:117]
	v_mfma_f32_16x16x32_bf16 v[106:109], v[136:139], v[192:195], v[106:109]
	v_mfma_f32_16x16x32_bf16 v[106:109], v[144:147], v[196:199], v[106:109]
	v_mfma_f32_16x16x32_bf16 v[102:105], v[148:151], v[192:195], v[102:105]
	v_mfma_f32_16x16x32_bf16 v[102:105], v[152:155], v[196:199], v[102:105]
	v_mfma_f32_16x16x32_bf16 v[90:93], v[136:139], v[200:203], v[90:93]
	v_mfma_f32_16x16x32_bf16 v[90:93], v[144:147], v[204:207], v[90:93]
	v_mfma_f32_16x16x32_bf16 v[86:89], v[148:151], v[200:203], v[86:89]
	v_mfma_f32_16x16x32_bf16 v[86:89], v[152:155], v[204:207], v[86:89]
	v_mfma_f32_16x16x32_bf16 v[74:77], v[136:139], v[216:219], v[74:77]
	v_mfma_f32_16x16x32_bf16 v[74:77], v[144:147], v[220:223], v[74:77]
	v_mfma_f32_16x16x32_bf16 v[70:73], v[148:151], v[216:219], v[70:73]
	v_mfma_f32_16x16x32_bf16 v[70:73], v[152:155], v[220:223], v[70:73]
	v_mfma_f32_16x16x32_bf16 v[126:129], v[168:171], v[184:187], v[126:129]
	v_mfma_f32_16x16x32_bf16 v[126:129], v[172:175], v[188:191], v[126:129]
	v_mfma_f32_16x16x32_bf16 v[118:121], v[176:179], v[184:187], v[118:121]
	v_mfma_f32_16x16x32_bf16 v[118:121], v[180:183], v[188:191], v[118:121]
	v_mfma_f32_16x16x32_bf16 v[110:113], v[168:171], v[192:195], v[110:113]
	v_mfma_f32_16x16x32_bf16 v[110:113], v[172:175], v[196:199], v[110:113]
	v_mfma_f32_16x16x32_bf16 v[98:101], v[176:179], v[192:195], v[98:101]
	v_mfma_f32_16x16x32_bf16 v[98:101], v[180:183], v[196:199], v[98:101]
	v_mfma_f32_16x16x32_bf16 v[94:97], v[168:171], v[200:203], v[94:97]
	v_mfma_f32_16x16x32_bf16 v[94:97], v[172:175], v[204:207], v[94:97]
	v_mfma_f32_16x16x32_bf16 v[82:85], v[176:179], v[200:203], v[82:85]
	v_mfma_f32_16x16x32_bf16 v[82:85], v[180:183], v[204:207], v[82:85]
	v_mfma_f32_16x16x32_bf16 v[78:81], v[168:171], v[216:219], v[78:81]
	v_mfma_f32_16x16x32_bf16 v[78:81], v[172:175], v[220:223], v[78:81]
	v_mfma_f32_16x16x32_bf16 v[66:69], v[176:179], v[216:219], v[66:69]
	v_mfma_f32_16x16x32_bf16 v[66:69], v[180:183], v[220:223], v[66:69]
	s_barrier
	s_add_i32 s16, s44, s61
	s_mov_b32 m0, s16
	s_add_u32 s14, s14, 0x80
	s_addc_u32 s15, s15, 0
	s_add_u32 vcc_lo, vcc_lo, 0x80
	s_addc_u32 vcc_hi, vcc_hi, 0
	ds_read_b128 v[184:187], v142 offset:49152
	ds_read_b128 v[188:191], v142 offset:50176
	ds_read_b128 v[192:195], v142 offset:51200
	ds_read_b128 v[196:199], v142 offset:52224
	ds_read_b128 v[200:203], v142 offset:53248
	ds_read_b128 v[204:207], v142 offset:54272
	ds_read_b128 v[216:219], v142 offset:55296
	ds_read_b128 v[220:223], v142 offset:56320
	global_load_lds_dwordx4 v158, s[14:15]
	s_add_i32 m0, s16, 0x2000
	s_nop 0
	global_load_lds_dwordx4 v134, s[14:15]
	s_add_u32 s14, s14, 0x80000
	s_addc_u32 s15, s15, 0
	s_add_i32 s16, s45, s61
	s_mov_b32 m0, s16
	s_nop 0
	global_load_lds_dwordx4 v158, s[14:15]
	s_add_i32 m0, s16, 0x2000
	s_nop 0
	global_load_lds_dwordx4 v134, s[14:15]
	s_mov_b32 m0, s26
	s_nop 0
	global_load_lds_dwordx4 v130, vcc
	s_mov_b32 m0, s27
	s_nop 0
	global_load_lds_dwordx4 v132, vcc
	s_waitcnt vmcnt(8)
	s_waitcnt lgkmcnt(0)
	s_barrier
	s_waitcnt lgkmcnt(0)
	v_mfma_f32_16x16x32_bf16 v[58:61], v[136:139], v[184:187], v[58:61]
	v_mfma_f32_16x16x32_bf16 v[58:61], v[144:147], v[188:191], v[58:61]
	v_mfma_f32_16x16x32_bf16 v[54:57], v[148:151], v[184:187], v[54:57]
	v_mfma_f32_16x16x32_bf16 v[54:57], v[152:155], v[188:191], v[54:57]
	v_mfma_f32_16x16x32_bf16 v[42:45], v[136:139], v[192:195], v[42:45]
	v_mfma_f32_16x16x32_bf16 v[42:45], v[144:147], v[196:199], v[42:45]
	v_mfma_f32_16x16x32_bf16 v[38:41], v[148:151], v[192:195], v[38:41]
	v_mfma_f32_16x16x32_bf16 v[38:41], v[152:155], v[196:199], v[38:41]
	v_mfma_f32_16x16x32_bf16 v[26:29], v[136:139], v[200:203], v[26:29]
	v_mfma_f32_16x16x32_bf16 v[26:29], v[144:147], v[204:207], v[26:29]
	v_mfma_f32_16x16x32_bf16 v[22:25], v[148:151], v[200:203], v[22:25]
	v_mfma_f32_16x16x32_bf16 v[22:25], v[152:155], v[204:207], v[22:25]
	v_mfma_f32_16x16x32_bf16 v[10:13], v[136:139], v[216:219], v[10:13]
	v_mfma_f32_16x16x32_bf16 v[10:13], v[144:147], v[220:223], v[10:13]
	v_mfma_f32_16x16x32_bf16 v[2:5], v[148:151], v[216:219], v[2:5]
	v_mfma_f32_16x16x32_bf16 v[2:5], v[152:155], v[220:223], v[2:5]
	v_mfma_f32_16x16x32_bf16 v[62:65], v[168:171], v[184:187], v[62:65]
	v_mfma_f32_16x16x32_bf16 v[62:65], v[172:175], v[188:191], v[62:65]
	v_mfma_f32_16x16x32_bf16 v[50:53], v[176:179], v[184:187], v[50:53]
	v_mfma_f32_16x16x32_bf16 v[50:53], v[180:183], v[188:191], v[50:53]
	v_mfma_f32_16x16x32_bf16 v[46:49], v[168:171], v[192:195], v[46:49]
	v_mfma_f32_16x16x32_bf16 v[46:49], v[172:175], v[196:199], v[46:49]
	v_mfma_f32_16x16x32_bf16 v[34:37], v[176:179], v[192:195], v[34:37]
	v_mfma_f32_16x16x32_bf16 v[34:37], v[180:183], v[196:199], v[34:37]
	v_mfma_f32_16x16x32_bf16 v[30:33], v[168:171], v[200:203], v[30:33]
	v_mfma_f32_16x16x32_bf16 v[30:33], v[172:175], v[204:207], v[30:33]
	v_mfma_f32_16x16x32_bf16 v[18:21], v[176:179], v[200:203], v[18:21]
	v_mfma_f32_16x16x32_bf16 v[18:21], v[180:183], v[204:207], v[18:21]
	v_mfma_f32_16x16x32_bf16 v[14:17], v[168:171], v[216:219], v[14:17]
	v_mfma_f32_16x16x32_bf16 v[14:17], v[172:175], v[220:223], v[14:17]
	v_mfma_f32_16x16x32_bf16 v[6:9], v[176:179], v[216:219], v[6:9]
	v_mfma_f32_16x16x32_bf16 v[6:9], v[180:183], v[220:223], v[6:9]
	s_barrier
	s_cmp_gt_u32 s35, 29
	s_mov_b32 s35, s54
	s_cbranch_scc1 .LBB0_279
